# rw_scan stage B: Tinv rows paired in v_pk_fma_f32 with SGPR-pair M operands (on top of v6 stage-B hand schedule)
# speedup vs baseline: 1.0068x; 1.0068x over previous
; #define LAS __attribute__((address_space(3)))
; __device__ __forceinline__ bf16_t f2bf(float f) { return (bf16_t)(cvt_pk_bf16(f, 0.f) & 0xffffu); }
; __device__ __forceinline__ void rw_scan(LAS unsigned char* L, const bf16_t* Rg, const bf16_t* Kg, const bf16_t* Vg, const bf16_t* VF, const bf16_t* LO, const bf16_t* wlbT, const bf16_t* albT, const bf16_t* vlbT, ...
;     ...
;                 if ((wid & 1) == 0) { asm volatile("" ::: "memory");
;                     const int c = lane & 15; float tcol[16];
; #pragma unroll
;                     for (int i = 0; i < 16; ++i) { float acc0 = (i == c) ? 1.f : 0.f, acc1 = 0.f;
; #pragma unroll
;                         for (int j4 = 0; j4 < 4; ++j4) { if (j4 * 4 < i) { const f32x4 m4 = *(const LAS f32x4*)(MM + (sc * 16 + i) * 20 + j4 * 4);
; #pragma unroll
;                                 for (int jr = 0; jr < 4; ++jr) { const int j = j4 * 4 + jr; if (j < i) { if (jr & 1) acc1 -= m4[jr] * tcol[j]; else acc0 -= m4[jr] * tcol[j]; } } } }
;                         tcol[i] = acc0 + acc1; }
;                     if (lane < 16) {
; #pragma unroll
;                         for (int i = 0; i < 16; ++i) TI[(sc * 16 + i) * 32 + 8 * (c >> 2) + (c & 3)] = f2bf(-tcol[i]); } }
.LBB0_123:
	s_waitcnt lgkmcnt(0)
	s_barrier
	v_cndmask_b32_e64 v1, 0, 1, s[24:25]
	v_cmp_ne_u32_e64 s[74:75], 1, v1
	s_andn2_b64 vcc, exec, s[24:25]
	s_cbranch_vccnz .LBB0_147
	s_and_b64 vcc, exec, s[50:51]
	s_cbranch_vccnz .Lp2_odd_h1
	ds_read_b128 v[212:215], v156 offset:53248
	ds_read_b128 v[216:219], v146
	ds_read_b128 v[230:233], v156 offset:53312
	ds_read_b128 v[234:237], v146 offset:64
	s_waitcnt lgkmcnt(2)
	v_mfma_f32_16x16x32_bf16 v[40:43], v[212:215], v[216:219], 0
	s_waitcnt lgkmcnt(0)
	v_mfma_f32_16x16x32_bf16 v[40:43], v[230:233], v[234:237], v[40:43]
	s_and_saveexec_b64 s[26:27], s[48:49]
	s_nop 7
	v_readlane_b32 s2, v41, 0
	v_readlane_b32 s4, v42, 0
	v_readlane_b32 s5, v43, 0
	v_readlane_b32 s6, v42, 1
	v_readlane_b32 s7, v43, 1
	v_readlane_b32 s8, v43, 2
	v_fma_f32 v45, -s2, v157, v158
	v_cvt_pk_bf16_f32 v1, -v45, v45
	ds_write_b16 v178, v1 offset:64
	v_readlane_b32 s10, v40, 16
	v_readlane_b32 s11, v41, 16
	v_pk_fma_f32 v[212:213], s[4:5], v[156:157], v[160:161] op_sel:[0,1,0] neg_lo:[1,0,0] neg_hi:[1,0,0]
	v_readlane_b32 s98, v40, 17
	v_readlane_b32 s99, v41, 17
	v_pk_fma_f32 v[214:215], s[6:7], v[44:45], 0 op_sel:[0,1,0] op_sel_hi:[1,1,0] neg_lo:[1,0,0] neg_hi:[1,0,0]
	v_add_f32_e32 v46, v212, v214
	v_cvt_pk_bf16_f32 v1, -v46, v46
	ds_write_b16 v178, v1 offset:128
	v_readlane_b32 s2, v40, 18
	v_readlane_b32 s3, v41, 18
	v_fma_f32 v213, -s8, v46, v213
	v_add_f32_e32 v47, v213, v215
	v_cvt_pk_bf16_f32 v1, -v47, v47
	ds_write_b16 v178, v1 offset:192
	v_readlane_b32 s4, v40, 19
	v_readlane_b32 s5, v41, 19
	v_pk_fma_f32 v[216:217], s[10:11], v[156:157], v[162:163] op_sel:[0,1,0] neg_lo:[1,0,0] neg_hi:[1,0,0]
	v_readlane_b32 s6, v41, 20
	v_pk_fma_f32 v[218:219], s[98:99], v[44:45], 0 op_sel:[0,1,0] op_sel_hi:[1,1,0] neg_lo:[1,0,0] neg_hi:[1,0,0]
	v_readlane_b32 s8, v42, 16
	v_readlane_b32 s9, v43, 16
	v_pk_fma_f32 v[216:217], s[2:3], v[46:47], v[216:217] op_sel_hi:[1,0,1] neg_lo:[1,0,0] neg_hi:[1,0,0]
	v_readlane_b32 s10, v42, 17
	v_readlane_b32 s11, v43, 17
	v_pk_fma_f32 v[218:219], s[4:5], v[46:47], v[218:219] op_sel:[0,1,0] neg_lo:[1,0,0] neg_hi:[1,0,0]
	v_add_f32_e32 v48, v216, v218
	v_cvt_pk_bf16_f32 v1, -v48, v48
	ds_write_b16 v178, v1 offset:256
	v_readlane_b32 s98, v42, 18
	v_readlane_b32 s99, v43, 18
	v_fma_f32 v217, -s6, v48, v217
	v_add_f32_e32 v49, v217, v219
	v_cvt_pk_bf16_f32 v1, -v49, v49
	ds_write_b16 v178, v1 offset:320
	v_readlane_b32 s2, v42, 19
	v_readlane_b32 s3, v43, 19
	v_pk_fma_f32 v[212:213], s[8:9], v[156:157], v[164:165] op_sel:[0,1,0] neg_lo:[1,0,0] neg_hi:[1,0,0]
	v_readlane_b32 s4, v42, 20
	v_readlane_b32 s5, v43, 20
	v_pk_fma_f32 v[214:215], s[10:11], v[44:45], 0 op_sel:[0,1,0] op_sel_hi:[1,1,0] neg_lo:[1,0,0] neg_hi:[1,0,0]
	v_readlane_b32 s6, v42, 21
	v_readlane_b32 s7, v43, 21
	v_pk_fma_f32 v[212:213], s[98:99], v[46:47], v[212:213] op_sel_hi:[1,0,1] neg_lo:[1,0,0] neg_hi:[1,0,0]
	v_readlane_b32 s8, v43, 22
	v_pk_fma_f32 v[214:215], s[2:3], v[46:47], v[214:215] op_sel:[0,1,0] neg_lo:[1,0,0] neg_hi:[1,0,0]
	v_readlane_b32 s10, v40, 32
	v_readlane_b32 s11, v41, 32
	v_pk_fma_f32 v[212:213], s[4:5], v[48:49], v[212:213] op_sel_hi:[1,0,1] neg_lo:[1,0,0] neg_hi:[1,0,0]
	v_readlane_b32 s98, v40, 33
	v_readlane_b32 s99, v41, 33
	v_pk_fma_f32 v[214:215], s[6:7], v[48:49], v[214:215] op_sel:[0,1,0] neg_lo:[1,0,0] neg_hi:[1,0,0]
	v_add_f32_e32 v50, v212, v214
	v_cvt_pk_bf16_f32 v1, -v50, v50
	ds_write_b16 v178, v1 offset:384
	v_readlane_b32 s2, v40, 34
	v_readlane_b32 s3, v41, 34
	v_fma_f32 v213, -s8, v50, v213
	v_add_f32_e32 v51, v213, v215
	v_cvt_pk_bf16_f32 v1, -v51, v51
	ds_write_b16 v178, v1 offset:448
	v_readlane_b32 s4, v40, 35
	v_readlane_b32 s5, v41, 35
	v_pk_fma_f32 v[216:217], s[10:11], v[156:157], v[166:167] op_sel:[0,1,0] neg_lo:[1,0,0] neg_hi:[1,0,0]
	v_readlane_b32 s6, v40, 36
	v_readlane_b32 s7, v41, 36
	v_pk_fma_f32 v[218:219], s[98:99], v[44:45], 0 op_sel:[0,1,0] op_sel_hi:[1,1,0] neg_lo:[1,0,0] neg_hi:[1,0,0]
	v_readlane_b32 s8, v40, 37
	v_readlane_b32 s9, v41, 37
	v_pk_fma_f32 v[216:217], s[2:3], v[46:47], v[216:217] op_sel_hi:[1,0,1] neg_lo:[1,0,0] neg_hi:[1,0,0]
	v_readlane_b32 s10, v40, 38
	v_readlane_b32 s11, v41, 38
	v_pk_fma_f32 v[218:219], s[4:5], v[46:47], v[218:219] op_sel:[0,1,0] neg_lo:[1,0,0] neg_hi:[1,0,0]
	v_readlane_b32 s98, v40, 39
	v_readlane_b32 s99, v41, 39
	v_pk_fma_f32 v[216:217], s[6:7], v[48:49], v[216:217] op_sel_hi:[1,0,1] neg_lo:[1,0,0] neg_hi:[1,0,0]
	v_readlane_b32 s2, v41, 40
	v_pk_fma_f32 v[218:219], s[8:9], v[48:49], v[218:219] op_sel:[0,1,0] neg_lo:[1,0,0] neg_hi:[1,0,0]
	v_readlane_b32 s4, v42, 32
	v_readlane_b32 s5, v43, 32
	v_pk_fma_f32 v[216:217], s[10:11], v[50:51], v[216:217] op_sel_hi:[1,0,1] neg_lo:[1,0,0] neg_hi:[1,0,0]
	v_readlane_b32 s6, v42, 33
	v_readlane_b32 s7, v43, 33
	v_pk_fma_f32 v[218:219], s[98:99], v[50:51], v[218:219] op_sel:[0,1,0] neg_lo:[1,0,0] neg_hi:[1,0,0]
	v_add_f32_e32 v52, v216, v218
	v_cvt_pk_bf16_f32 v1, -v52, v52
	ds_write_b16 v178, v1 offset:512
	v_readlane_b32 s8, v42, 34
	v_readlane_b32 s9, v43, 34
	v_fma_f32 v217, -s2, v52, v217
	v_add_f32_e32 v53, v217, v219
	v_cvt_pk_bf16_f32 v1, -v53, v53
	ds_write_b16 v178, v1 offset:576
	v_readlane_b32 s10, v42, 35
	v_readlane_b32 s11, v43, 35
	v_pk_fma_f32 v[212:213], s[4:5], v[156:157], v[168:169] op_sel:[0,1,0] neg_lo:[1,0,0] neg_hi:[1,0,0]
	v_readlane_b32 s98, v42, 36
	v_readlane_b32 s99, v43, 36
	v_pk_fma_f32 v[214:215], s[6:7], v[44:45], 0 op_sel:[0,1,0] op_sel_hi:[1,1,0] neg_lo:[1,0,0] neg_hi:[1,0,0]
	v_readlane_b32 s2, v42, 37
	v_readlane_b32 s3, v43, 37
	v_pk_fma_f32 v[212:213], s[8:9], v[46:47], v[212:213] op_sel_hi:[1,0,1] neg_lo:[1,0,0] neg_hi:[1,0,0]
; #define LAS __attribute__((address_space(3)))
; __device__ __forceinline__ bf16_t f2bf(float f) { return (bf16_t)(cvt_pk_bf16(f, 0.f) & 0xffffu); }
; __device__ __forceinline__ void rw_scan(LAS unsigned char* L, const bf16_t* Rg, const bf16_t* Kg, const bf16_t* Vg, const bf16_t* VF, const bf16_t* LO, const bf16_t* wlbT, const bf16_t* albT, const bf16_t* vlbT, ...
;     ...
;                 if ((wid & 1) == 0) { asm volatile("" ::: "memory");
;                     const int c = lane & 15; float tcol[16];
; #pragma unroll
;                     for (int i = 0; i < 16; ++i) { float acc0 = (i == c) ? 1.f : 0.f, acc1 = 0.f;
; #pragma unroll
;                         for (int j4 = 0; j4 < 4; ++j4) { if (j4 * 4 < i) { const f32x4 m4 = *(const LAS f32x4*)(MM + (sc * 16 + i) * 20 + j4 * 4);
; #pragma unroll
;                                 for (int jr = 0; jr < 4; ++jr) { const int j = j4 * 4 + jr; if (j < i) { if (jr & 1) acc1 -= m4[jr] * tcol[j]; else acc0 -= m4[jr] * tcol[j]; } } } }
;                         tcol[i] = acc0 + acc1; }
;                     if (lane < 16) {
; #pragma unroll
;                         for (int i = 0; i < 16; ++i) TI[(sc * 16 + i) * 32 + 8 * (c >> 2) + (c & 3)] = f2bf(-tcol[i]); } }
	v_readlane_b32 s4, v42, 38
	v_readlane_b32 s5, v43, 38
	v_pk_fma_f32 v[214:215], s[10:11], v[46:47], v[214:215] op_sel:[0,1,0] neg_lo:[1,0,0] neg_hi:[1,0,0]
	v_readlane_b32 s6, v42, 39
	v_readlane_b32 s7, v43, 39
	v_pk_fma_f32 v[212:213], s[98:99], v[48:49], v[212:213] op_sel_hi:[1,0,1] neg_lo:[1,0,0] neg_hi:[1,0,0]
	v_readlane_b32 s8, v42, 40
	v_readlane_b32 s9, v43, 40
	v_pk_fma_f32 v[214:215], s[2:3], v[48:49], v[214:215] op_sel:[0,1,0] neg_lo:[1,0,0] neg_hi:[1,0,0]
	v_readlane_b32 s10, v42, 41
	v_readlane_b32 s11, v43, 41
	v_pk_fma_f32 v[212:213], s[4:5], v[50:51], v[212:213] op_sel_hi:[1,0,1] neg_lo:[1,0,0] neg_hi:[1,0,0]
	v_readlane_b32 s98, v43, 42
	v_pk_fma_f32 v[214:215], s[6:7], v[50:51], v[214:215] op_sel:[0,1,0] neg_lo:[1,0,0] neg_hi:[1,0,0]
	v_readlane_b32 s2, v40, 48
	v_readlane_b32 s3, v41, 48
	v_pk_fma_f32 v[212:213], s[8:9], v[52:53], v[212:213] op_sel_hi:[1,0,1] neg_lo:[1,0,0] neg_hi:[1,0,0]
	v_readlane_b32 s4, v40, 49
	v_readlane_b32 s5, v41, 49
	v_pk_fma_f32 v[214:215], s[10:11], v[52:53], v[214:215] op_sel:[0,1,0] neg_lo:[1,0,0] neg_hi:[1,0,0]
	v_add_f32_e32 v54, v212, v214
	v_cvt_pk_bf16_f32 v1, -v54, v54
	ds_write_b16 v178, v1 offset:640
	v_readlane_b32 s6, v40, 50
	v_readlane_b32 s7, v41, 50
	v_fma_f32 v213, -s98, v54, v213
	v_add_f32_e32 v55, v213, v215
	v_cvt_pk_bf16_f32 v1, -v55, v55
	ds_write_b16 v178, v1 offset:704
	v_readlane_b32 s8, v40, 51
	v_readlane_b32 s9, v41, 51
	v_pk_fma_f32 v[216:217], s[2:3], v[156:157], v[170:171] op_sel:[0,1,0] neg_lo:[1,0,0] neg_hi:[1,0,0]
	v_readlane_b32 s10, v40, 52
	v_readlane_b32 s11, v41, 52
	v_pk_fma_f32 v[218:219], s[4:5], v[44:45], 0 op_sel:[0,1,0] op_sel_hi:[1,1,0] neg_lo:[1,0,0] neg_hi:[1,0,0]
	v_readlane_b32 s98, v40, 53
	v_readlane_b32 s99, v41, 53
	v_pk_fma_f32 v[216:217], s[6:7], v[46:47], v[216:217] op_sel_hi:[1,0,1] neg_lo:[1,0,0] neg_hi:[1,0,0]
	v_readlane_b32 s2, v40, 54
	v_readlane_b32 s3, v41, 54
	v_pk_fma_f32 v[218:219], s[8:9], v[46:47], v[218:219] op_sel:[0,1,0] neg_lo:[1,0,0] neg_hi:[1,0,0]
	v_readlane_b32 s4, v40, 55
	v_readlane_b32 s5, v41, 55
	v_pk_fma_f32 v[216:217], s[10:11], v[48:49], v[216:217] op_sel_hi:[1,0,1] neg_lo:[1,0,0] neg_hi:[1,0,0]
	v_readlane_b32 s6, v40, 56
	v_readlane_b32 s7, v41, 56
	v_pk_fma_f32 v[218:219], s[98:99], v[48:49], v[218:219] op_sel:[0,1,0] neg_lo:[1,0,0] neg_hi:[1,0,0]
	v_readlane_b32 s8, v40, 57
	v_readlane_b32 s9, v41, 57
	v_pk_fma_f32 v[216:217], s[2:3], v[50:51], v[216:217] op_sel_hi:[1,0,1] neg_lo:[1,0,0] neg_hi:[1,0,0]
	v_readlane_b32 s10, v40, 58
	v_readlane_b32 s11, v41, 58
	v_pk_fma_f32 v[218:219], s[4:5], v[50:51], v[218:219] op_sel:[0,1,0] neg_lo:[1,0,0] neg_hi:[1,0,0]
	v_readlane_b32 s98, v40, 59
	v_readlane_b32 s99, v41, 59
	v_pk_fma_f32 v[216:217], s[6:7], v[52:53], v[216:217] op_sel_hi:[1,0,1] neg_lo:[1,0,0] neg_hi:[1,0,0]
	v_readlane_b32 s2, v41, 60
	v_pk_fma_f32 v[218:219], s[8:9], v[52:53], v[218:219] op_sel:[0,1,0] neg_lo:[1,0,0] neg_hi:[1,0,0]
	v_readlane_b32 s4, v42, 48
	v_readlane_b32 s5, v43, 48
	v_pk_fma_f32 v[216:217], s[10:11], v[54:55], v[216:217] op_sel_hi:[1,0,1] neg_lo:[1,0,0] neg_hi:[1,0,0]
	v_readlane_b32 s6, v42, 49
	v_readlane_b32 s7, v43, 49
	v_pk_fma_f32 v[218:219], s[98:99], v[54:55], v[218:219] op_sel:[0,1,0] neg_lo:[1,0,0] neg_hi:[1,0,0]
	v_add_f32_e32 v56, v216, v218
	v_cvt_pk_bf16_f32 v1, -v56, v56
	ds_write_b16 v178, v1 offset:768
	v_readlane_b32 s8, v42, 50
	v_readlane_b32 s9, v43, 50
	v_fma_f32 v217, -s2, v56, v217
	v_add_f32_e32 v57, v217, v219
	v_cvt_pk_bf16_f32 v1, -v57, v57
	ds_write_b16 v178, v1 offset:832
	v_readlane_b32 s10, v42, 51
	v_readlane_b32 s11, v43, 51
	v_pk_fma_f32 v[212:213], s[4:5], v[156:157], v[172:173] op_sel:[0,1,0] neg_lo:[1,0,0] neg_hi:[1,0,0]
	v_readlane_b32 s98, v42, 52
	v_readlane_b32 s99, v43, 52
	v_pk_fma_f32 v[214:215], s[6:7], v[44:45], 0 op_sel:[0,1,0] op_sel_hi:[1,1,0] neg_lo:[1,0,0] neg_hi:[1,0,0]
	v_readlane_b32 s2, v42, 53
	v_readlane_b32 s3, v43, 53
	v_pk_fma_f32 v[212:213], s[8:9], v[46:47], v[212:213] op_sel_hi:[1,0,1] neg_lo:[1,0,0] neg_hi:[1,0,0]
	v_readlane_b32 s4, v42, 54
	v_readlane_b32 s5, v43, 54
	v_pk_fma_f32 v[214:215], s[10:11], v[46:47], v[214:215] op_sel:[0,1,0] neg_lo:[1,0,0] neg_hi:[1,0,0]
	v_readlane_b32 s6, v42, 55
	v_readlane_b32 s7, v43, 55
	v_pk_fma_f32 v[212:213], s[98:99], v[48:49], v[212:213] op_sel_hi:[1,0,1] neg_lo:[1,0,0] neg_hi:[1,0,0]
	v_readlane_b32 s8, v42, 56
	v_readlane_b32 s9, v43, 56
	v_pk_fma_f32 v[214:215], s[2:3], v[48:49], v[214:215] op_sel:[0,1,0] neg_lo:[1,0,0] neg_hi:[1,0,0]
	v_readlane_b32 s10, v42, 57
	v_readlane_b32 s11, v43, 57
	v_pk_fma_f32 v[212:213], s[4:5], v[50:51], v[212:213] op_sel_hi:[1,0,1] neg_lo:[1,0,0] neg_hi:[1,0,0]
	v_readlane_b32 s98, v42, 58
	v_readlane_b32 s99, v43, 58
	v_pk_fma_f32 v[214:215], s[6:7], v[50:51], v[214:215] op_sel:[0,1,0] neg_lo:[1,0,0] neg_hi:[1,0,0]
	v_readlane_b32 s2, v42, 59
	v_readlane_b32 s3, v43, 59
	v_pk_fma_f32 v[212:213], s[8:9], v[52:53], v[212:213] op_sel_hi:[1,0,1] neg_lo:[1,0,0] neg_hi:[1,0,0]
	v_readlane_b32 s4, v42, 60
	v_readlane_b32 s5, v43, 60
	v_pk_fma_f32 v[214:215], s[10:11], v[52:53], v[214:215] op_sel:[0,1,0] neg_lo:[1,0,0] neg_hi:[1,0,0]
	v_readlane_b32 s6, v42, 61
	v_readlane_b32 s7, v43, 61
	v_pk_fma_f32 v[212:213], s[98:99], v[54:55], v[212:213] op_sel_hi:[1,0,1] neg_lo:[1,0,0] neg_hi:[1,0,0]
	v_readlane_b32 s8, v43, 62
	v_pk_fma_f32 v[214:215], s[2:3], v[54:55], v[214:215] op_sel:[0,1,0] neg_lo:[1,0,0] neg_hi:[1,0,0]
	v_pk_fma_f32 v[212:213], s[4:5], v[56:57], v[212:213] op_sel_hi:[1,0,1] neg_lo:[1,0,0] neg_hi:[1,0,0]
	v_pk_fma_f32 v[214:215], s[6:7], v[56:57], v[214:215] op_sel:[0,1,0] neg_lo:[1,0,0] neg_hi:[1,0,0]
	v_add_f32_e32 v58, v212, v214
	v_cvt_pk_bf16_f32 v1, -v58, v58
	ds_write_b16 v178, v1 offset:896
	v_fma_f32 v213, -s8, v58, v213
	v_add_f32_e32 v59, v213, v215
	v_cvt_pk_bf16_f32 v1, -v59, v59
	ds_write_b16 v178, v1 offset:960
	ds_write_b16 v178, v174
	s_or_b64 exec, exec, s[26:27]
	s_branch .LBB0_147

; #define LAS __attribute__((address_space(3)))
; __device__ __forceinline__ void rw_scan(LAS unsigned char* L, const bf16_t* Rg, const bf16_t* Kg, const bf16_t* Vg, const bf16_t* VF, const bf16_t* LO, const bf16_t* wlbT, const bf16_t* albT, const bf16_t* vlbT, ...
;     ...
;             if (m < 256) { const int sc = wid >> 1;
; #pragma unroll
;                 for (int ml = 0; ml < 3; ++ml) { const int mat = (wid & 1) ? ml + 1 : 0; if ((wid & 1) == 0 && ml > 0) break;     const LAS bf16_t* Am = (mat < 2) ? KQ : RQ; const LAS bf16_t* Bm = (mat & 1) ? KD : BD;
;                     f32x4 acc = {0.f, 0.f, 0.f, 0.f};
;                     acc = mma16(lfrag(Am, 72, sc * 16 + fr, 8 * fq), lfrag(Bm, 72, sc * 16 + fr, 8 * fq), acc);
;                     acc = mma16(lfrag(Am, 72, sc * 16 + fr, 32 + 8 * fq), lfrag(Bm, 72, sc * 16 + fr, 32 + 8 * fq), acc);
; #pragma unroll
;                     for (int r = 0; r < 4; ++r) { const int t = 4 * fq + r, sidx = fr; const bool keep = (mat < 2) ? (sidx < t) : (sidx <= t); const float val = keep ? acc[r] : 0.f;
;                         if (mat == 0) MM[(sc * 16 + t) * 20 + sidx] = val;
;                         else if (mat == 1) NA[(sc * 16 + t) * 32 + 8 * (sidx >> 2) + 4 + (sidx & 3)] = f2bf(val);
;                         else if (mat == 2) AR[(sc * 16 + t) * 40 + 8 * (sidx >> 2) + 2 * (sidx & 3)] = f2bf(val);
;                         else AR[(sc * 16 + t) * 40 + 8 * (sidx >> 2) + 2 * (sidx & 3) + 1] = f2bf(val); } }
;                 if ((wid & 1) == 0) { asm volatile("" ::: "memory");
;                     const int c = lane & 15; float tcol[16];
; #pragma unroll
;                     for (int i = 0; i < 16; ++i) { float acc0 = (i == c) ? 1.f : 0.f, acc1 = 0.f;
; #pragma unroll
;                         for (int j4 = 0; j4 < 4; ++j4) { if (j4 * 4 < i) { const f32x4 m4 = *(const LAS f32x4*)(MM + (sc * 16 + i) * 20 + j4 * 4);
; #pragma unroll
;                                 for (int jr = 0; jr < 4; ++jr) { const int j = j4 * 4 + jr; if (j < i) { if (jr & 1) acc1 -= m4[jr] * tcol[j]; else acc0 -= m4[jr] * tcol[j]; } } } }
;                         tcol[i] = acc0 + acc1; }
;                     if (lane < 16) {
; #pragma unroll
;                         for (int i = 0; i < 16; ++i) TI[(sc * 16 + i) * 32 + 8 * (c >> 2) + (c & 3)] = f2bf(-tcol[i]); } }
.LBB0_182:
	s_waitcnt lgkmcnt(0)
	s_barrier
	s_and_b64 vcc, exec, s[74:75]
	s_cbranch_vccnz .LBB0_90
	s_and_b64 vcc, exec, s[50:51]
	s_cbranch_vccnz .Lp2_odd_h2
	ds_read_b128 v[212:215], v184
	ds_read_b128 v[216:219], v146
	ds_read_b128 v[230:233], v184 offset:64
	ds_read_b128 v[234:237], v146 offset:64
	s_waitcnt lgkmcnt(2)
	v_mfma_f32_16x16x32_bf16 v[40:43], v[212:215], v[216:219], 0
	s_waitcnt lgkmcnt(0)
	v_mfma_f32_16x16x32_bf16 v[40:43], v[230:233], v[234:237], v[40:43]
	s_and_saveexec_b64 s[24:25], s[48:49]
	s_nop 7
	v_readlane_b32 s2, v41, 0
	v_readlane_b32 s4, v42, 0
	v_readlane_b32 s5, v43, 0
	v_readlane_b32 s6, v42, 1
	v_readlane_b32 s7, v43, 1
	v_readlane_b32 s8, v43, 2
	v_fma_f32 v45, -s2, v157, v158
	v_cvt_pk_bf16_f32 v1, -v45, v45
	ds_write_b16 v186, v1 offset:64
	v_readlane_b32 s10, v40, 16
	v_readlane_b32 s11, v41, 16
	v_pk_fma_f32 v[212:213], s[4:5], v[156:157], v[160:161] op_sel:[0,1,0] neg_lo:[1,0,0] neg_hi:[1,0,0]
	v_readlane_b32 s98, v40, 17
	v_readlane_b32 s99, v41, 17
	v_pk_fma_f32 v[214:215], s[6:7], v[44:45], 0 op_sel:[0,1,0] op_sel_hi:[1,1,0] neg_lo:[1,0,0] neg_hi:[1,0,0]
	v_add_f32_e32 v46, v212, v214
	v_cvt_pk_bf16_f32 v1, -v46, v46
	ds_write_b16 v186, v1 offset:128
	v_readlane_b32 s2, v40, 18
	v_readlane_b32 s3, v41, 18
	v_fma_f32 v213, -s8, v46, v213
	v_add_f32_e32 v47, v213, v215
	v_cvt_pk_bf16_f32 v1, -v47, v47
	ds_write_b16 v186, v1 offset:192
	v_readlane_b32 s4, v40, 19
	v_readlane_b32 s5, v41, 19
	v_pk_fma_f32 v[216:217], s[10:11], v[156:157], v[162:163] op_sel:[0,1,0] neg_lo:[1,0,0] neg_hi:[1,0,0]
	v_readlane_b32 s6, v41, 20
	v_pk_fma_f32 v[218:219], s[98:99], v[44:45], 0 op_sel:[0,1,0] op_sel_hi:[1,1,0] neg_lo:[1,0,0] neg_hi:[1,0,0]
	v_readlane_b32 s8, v42, 16
	v_readlane_b32 s9, v43, 16
	v_pk_fma_f32 v[216:217], s[2:3], v[46:47], v[216:217] op_sel_hi:[1,0,1] neg_lo:[1,0,0] neg_hi:[1,0,0]
	v_readlane_b32 s10, v42, 17
	v_readlane_b32 s11, v43, 17
	v_pk_fma_f32 v[218:219], s[4:5], v[46:47], v[218:219] op_sel:[0,1,0] neg_lo:[1,0,0] neg_hi:[1,0,0]
	v_add_f32_e32 v48, v216, v218
	v_cvt_pk_bf16_f32 v1, -v48, v48
	ds_write_b16 v186, v1 offset:256
	v_readlane_b32 s98, v42, 18
	v_readlane_b32 s99, v43, 18
	v_fma_f32 v217, -s6, v48, v217
	v_add_f32_e32 v49, v217, v219
	v_cvt_pk_bf16_f32 v1, -v49, v49
	ds_write_b16 v186, v1 offset:320
	v_readlane_b32 s2, v42, 19
	v_readlane_b32 s3, v43, 19
	v_pk_fma_f32 v[212:213], s[8:9], v[156:157], v[164:165] op_sel:[0,1,0] neg_lo:[1,0,0] neg_hi:[1,0,0]
	v_readlane_b32 s4, v42, 20
	v_readlane_b32 s5, v43, 20
	v_pk_fma_f32 v[214:215], s[10:11], v[44:45], 0 op_sel:[0,1,0] op_sel_hi:[1,1,0] neg_lo:[1,0,0] neg_hi:[1,0,0]
	v_readlane_b32 s6, v42, 21
	v_readlane_b32 s7, v43, 21
	v_pk_fma_f32 v[212:213], s[98:99], v[46:47], v[212:213] op_sel_hi:[1,0,1] neg_lo:[1,0,0] neg_hi:[1,0,0]
	v_readlane_b32 s8, v43, 22
	v_pk_fma_f32 v[214:215], s[2:3], v[46:47], v[214:215] op_sel:[0,1,0] neg_lo:[1,0,0] neg_hi:[1,0,0]
	v_readlane_b32 s10, v40, 32
	v_readlane_b32 s11, v41, 32
	v_pk_fma_f32 v[212:213], s[4:5], v[48:49], v[212:213] op_sel_hi:[1,0,1] neg_lo:[1,0,0] neg_hi:[1,0,0]
	v_readlane_b32 s98, v40, 33
	v_readlane_b32 s99, v41, 33
	v_pk_fma_f32 v[214:215], s[6:7], v[48:49], v[214:215] op_sel:[0,1,0] neg_lo:[1,0,0] neg_hi:[1,0,0]
	v_add_f32_e32 v50, v212, v214
	v_cvt_pk_bf16_f32 v1, -v50, v50
	ds_write_b16 v186, v1 offset:384
	v_readlane_b32 s2, v40, 34
	v_readlane_b32 s3, v41, 34
	v_fma_f32 v213, -s8, v50, v213
	v_add_f32_e32 v51, v213, v215
	v_cvt_pk_bf16_f32 v1, -v51, v51
	ds_write_b16 v186, v1 offset:448
	v_readlane_b32 s4, v40, 35
	v_readlane_b32 s5, v41, 35
	v_pk_fma_f32 v[216:217], s[10:11], v[156:157], v[166:167] op_sel:[0,1,0] neg_lo:[1,0,0] neg_hi:[1,0,0]
	v_readlane_b32 s6, v40, 36
	v_readlane_b32 s7, v41, 36
	v_pk_fma_f32 v[218:219], s[98:99], v[44:45], 0 op_sel:[0,1,0] op_sel_hi:[1,1,0] neg_lo:[1,0,0] neg_hi:[1,0,0]
	v_readlane_b32 s8, v40, 37
	v_readlane_b32 s9, v41, 37
	v_pk_fma_f32 v[216:217], s[2:3], v[46:47], v[216:217] op_sel_hi:[1,0,1] neg_lo:[1,0,0] neg_hi:[1,0,0]
	v_readlane_b32 s10, v40, 38
	v_readlane_b32 s11, v41, 38
	v_pk_fma_f32 v[218:219], s[4:5], v[46:47], v[218:219] op_sel:[0,1,0] neg_lo:[1,0,0] neg_hi:[1,0,0]
	v_readlane_b32 s98, v40, 39
	v_readlane_b32 s99, v41, 39
	v_pk_fma_f32 v[216:217], s[6:7], v[48:49], v[216:217] op_sel_hi:[1,0,1] neg_lo:[1,0,0] neg_hi:[1,0,0]
	v_readlane_b32 s2, v41, 40
	v_pk_fma_f32 v[218:219], s[8:9], v[48:49], v[218:219] op_sel:[0,1,0] neg_lo:[1,0,0] neg_hi:[1,0,0]
	v_readlane_b32 s4, v42, 32
	v_readlane_b32 s5, v43, 32
	v_pk_fma_f32 v[216:217], s[10:11], v[50:51], v[216:217] op_sel_hi:[1,0,1] neg_lo:[1,0,0] neg_hi:[1,0,0]
	v_readlane_b32 s6, v42, 33
	v_readlane_b32 s7, v43, 33
	v_pk_fma_f32 v[218:219], s[98:99], v[50:51], v[218:219] op_sel:[0,1,0] neg_lo:[1,0,0] neg_hi:[1,0,0]
	v_add_f32_e32 v52, v216, v218
	v_cvt_pk_bf16_f32 v1, -v52, v52
	ds_write_b16 v186, v1 offset:512
	v_readlane_b32 s8, v42, 34
	v_readlane_b32 s9, v43, 34
	v_fma_f32 v217, -s2, v52, v217
	v_add_f32_e32 v53, v217, v219
	v_cvt_pk_bf16_f32 v1, -v53, v53
	ds_write_b16 v186, v1 offset:576
	v_readlane_b32 s10, v42, 35
	v_readlane_b32 s11, v43, 35
	v_pk_fma_f32 v[212:213], s[4:5], v[156:157], v[168:169] op_sel:[0,1,0] neg_lo:[1,0,0] neg_hi:[1,0,0]
	v_readlane_b32 s98, v42, 36
	v_readlane_b32 s99, v43, 36
	v_pk_fma_f32 v[214:215], s[6:7], v[44:45], 0 op_sel:[0,1,0] op_sel_hi:[1,1,0] neg_lo:[1,0,0] neg_hi:[1,0,0]
	v_readlane_b32 s2, v42, 37
	v_readlane_b32 s3, v43, 37
	v_pk_fma_f32 v[212:213], s[8:9], v[46:47], v[212:213] op_sel_hi:[1,0,1] neg_lo:[1,0,0] neg_hi:[1,0,0]
	v_readlane_b32 s4, v42, 38
	v_readlane_b32 s5, v43, 38
; #define LAS __attribute__((address_space(3)))
; __device__ __forceinline__ bf16_t f2bf(float f) { return (bf16_t)(cvt_pk_bf16(f, 0.f) & 0xffffu); }
; __device__ __forceinline__ void rw_scan(LAS unsigned char* L, const bf16_t* Rg, const bf16_t* Kg, const bf16_t* Vg, const bf16_t* VF, const bf16_t* LO, const bf16_t* wlbT, const bf16_t* albT, const bf16_t* vlbT, ...
;     ...
;                 if ((wid & 1) == 0) { asm volatile("" ::: "memory");
;                     const int c = lane & 15; float tcol[16];
; #pragma unroll
;                     for (int i = 0; i < 16; ++i) { float acc0 = (i == c) ? 1.f : 0.f, acc1 = 0.f;
; #pragma unroll
;                         for (int j4 = 0; j4 < 4; ++j4) { if (j4 * 4 < i) { const f32x4 m4 = *(const LAS f32x4*)(MM + (sc * 16 + i) * 20 + j4 * 4);
; #pragma unroll
;                                 for (int jr = 0; jr < 4; ++jr) { const int j = j4 * 4 + jr; if (j < i) { if (jr & 1) acc1 -= m4[jr] * tcol[j]; else acc0 -= m4[jr] * tcol[j]; } } } }
;                         tcol[i] = acc0 + acc1; }
;                     if (lane < 16) {
; #pragma unroll
;                         for (int i = 0; i < 16; ++i) TI[(sc * 16 + i) * 32 + 8 * (c >> 2) + (c & 3)] = f2bf(-tcol[i]); } }
	v_pk_fma_f32 v[214:215], s[10:11], v[46:47], v[214:215] op_sel:[0,1,0] neg_lo:[1,0,0] neg_hi:[1,0,0]
	v_readlane_b32 s6, v42, 39
	v_readlane_b32 s7, v43, 39
	v_pk_fma_f32 v[212:213], s[98:99], v[48:49], v[212:213] op_sel_hi:[1,0,1] neg_lo:[1,0,0] neg_hi:[1,0,0]
	v_readlane_b32 s8, v42, 40
	v_readlane_b32 s9, v43, 40
	v_pk_fma_f32 v[214:215], s[2:3], v[48:49], v[214:215] op_sel:[0,1,0] neg_lo:[1,0,0] neg_hi:[1,0,0]
	v_readlane_b32 s10, v42, 41
	v_readlane_b32 s11, v43, 41
	v_pk_fma_f32 v[212:213], s[4:5], v[50:51], v[212:213] op_sel_hi:[1,0,1] neg_lo:[1,0,0] neg_hi:[1,0,0]
	v_readlane_b32 s98, v43, 42
	v_pk_fma_f32 v[214:215], s[6:7], v[50:51], v[214:215] op_sel:[0,1,0] neg_lo:[1,0,0] neg_hi:[1,0,0]
	v_readlane_b32 s2, v40, 48
	v_readlane_b32 s3, v41, 48
	v_pk_fma_f32 v[212:213], s[8:9], v[52:53], v[212:213] op_sel_hi:[1,0,1] neg_lo:[1,0,0] neg_hi:[1,0,0]
	v_readlane_b32 s4, v40, 49
	v_readlane_b32 s5, v41, 49
	v_pk_fma_f32 v[214:215], s[10:11], v[52:53], v[214:215] op_sel:[0,1,0] neg_lo:[1,0,0] neg_hi:[1,0,0]
	v_add_f32_e32 v54, v212, v214
	v_cvt_pk_bf16_f32 v1, -v54, v54
	ds_write_b16 v186, v1 offset:640
	v_readlane_b32 s6, v40, 50
	v_readlane_b32 s7, v41, 50
	v_fma_f32 v213, -s98, v54, v213
	v_add_f32_e32 v55, v213, v215
	v_cvt_pk_bf16_f32 v1, -v55, v55
	ds_write_b16 v186, v1 offset:704
	v_readlane_b32 s8, v40, 51
	v_readlane_b32 s9, v41, 51
	v_pk_fma_f32 v[216:217], s[2:3], v[156:157], v[170:171] op_sel:[0,1,0] neg_lo:[1,0,0] neg_hi:[1,0,0]
	v_readlane_b32 s10, v40, 52
	v_readlane_b32 s11, v41, 52
	v_pk_fma_f32 v[218:219], s[4:5], v[44:45], 0 op_sel:[0,1,0] op_sel_hi:[1,1,0] neg_lo:[1,0,0] neg_hi:[1,0,0]
	v_readlane_b32 s98, v40, 53
	v_readlane_b32 s99, v41, 53
	v_pk_fma_f32 v[216:217], s[6:7], v[46:47], v[216:217] op_sel_hi:[1,0,1] neg_lo:[1,0,0] neg_hi:[1,0,0]
	v_readlane_b32 s2, v40, 54
	v_readlane_b32 s3, v41, 54
	v_pk_fma_f32 v[218:219], s[8:9], v[46:47], v[218:219] op_sel:[0,1,0] neg_lo:[1,0,0] neg_hi:[1,0,0]
	v_readlane_b32 s4, v40, 55
	v_readlane_b32 s5, v41, 55
	v_pk_fma_f32 v[216:217], s[10:11], v[48:49], v[216:217] op_sel_hi:[1,0,1] neg_lo:[1,0,0] neg_hi:[1,0,0]
	v_readlane_b32 s6, v40, 56
	v_readlane_b32 s7, v41, 56
	v_pk_fma_f32 v[218:219], s[98:99], v[48:49], v[218:219] op_sel:[0,1,0] neg_lo:[1,0,0] neg_hi:[1,0,0]
	v_readlane_b32 s8, v40, 57
	v_readlane_b32 s9, v41, 57
	v_pk_fma_f32 v[216:217], s[2:3], v[50:51], v[216:217] op_sel_hi:[1,0,1] neg_lo:[1,0,0] neg_hi:[1,0,0]
	v_readlane_b32 s10, v40, 58
	v_readlane_b32 s11, v41, 58
	v_pk_fma_f32 v[218:219], s[4:5], v[50:51], v[218:219] op_sel:[0,1,0] neg_lo:[1,0,0] neg_hi:[1,0,0]
	v_readlane_b32 s98, v40, 59
	v_readlane_b32 s99, v41, 59
	v_pk_fma_f32 v[216:217], s[6:7], v[52:53], v[216:217] op_sel_hi:[1,0,1] neg_lo:[1,0,0] neg_hi:[1,0,0]
	v_readlane_b32 s2, v41, 60
	v_pk_fma_f32 v[218:219], s[8:9], v[52:53], v[218:219] op_sel:[0,1,0] neg_lo:[1,0,0] neg_hi:[1,0,0]
	v_readlane_b32 s4, v42, 48
	v_readlane_b32 s5, v43, 48
	v_pk_fma_f32 v[216:217], s[10:11], v[54:55], v[216:217] op_sel_hi:[1,0,1] neg_lo:[1,0,0] neg_hi:[1,0,0]
	v_readlane_b32 s6, v42, 49
	v_readlane_b32 s7, v43, 49
	v_pk_fma_f32 v[218:219], s[98:99], v[54:55], v[218:219] op_sel:[0,1,0] neg_lo:[1,0,0] neg_hi:[1,0,0]
	v_add_f32_e32 v56, v216, v218
	v_cvt_pk_bf16_f32 v1, -v56, v56
	ds_write_b16 v186, v1 offset:768
	v_readlane_b32 s8, v42, 50
	v_readlane_b32 s9, v43, 50
	v_fma_f32 v217, -s2, v56, v217
	v_add_f32_e32 v57, v217, v219
	v_cvt_pk_bf16_f32 v1, -v57, v57
	ds_write_b16 v186, v1 offset:832
	v_readlane_b32 s10, v42, 51
	v_readlane_b32 s11, v43, 51
	v_pk_fma_f32 v[212:213], s[4:5], v[156:157], v[172:173] op_sel:[0,1,0] neg_lo:[1,0,0] neg_hi:[1,0,0]
	v_readlane_b32 s98, v42, 52
	v_readlane_b32 s99, v43, 52
	v_pk_fma_f32 v[214:215], s[6:7], v[44:45], 0 op_sel:[0,1,0] op_sel_hi:[1,1,0] neg_lo:[1,0,0] neg_hi:[1,0,0]
	v_readlane_b32 s2, v42, 53
	v_readlane_b32 s3, v43, 53
	v_pk_fma_f32 v[212:213], s[8:9], v[46:47], v[212:213] op_sel_hi:[1,0,1] neg_lo:[1,0,0] neg_hi:[1,0,0]
	v_readlane_b32 s4, v42, 54
	v_readlane_b32 s5, v43, 54
	v_pk_fma_f32 v[214:215], s[10:11], v[46:47], v[214:215] op_sel:[0,1,0] neg_lo:[1,0,0] neg_hi:[1,0,0]
	v_readlane_b32 s6, v42, 55
	v_readlane_b32 s7, v43, 55
	v_pk_fma_f32 v[212:213], s[98:99], v[48:49], v[212:213] op_sel_hi:[1,0,1] neg_lo:[1,0,0] neg_hi:[1,0,0]
	v_readlane_b32 s8, v42, 56
	v_readlane_b32 s9, v43, 56
	v_pk_fma_f32 v[214:215], s[2:3], v[48:49], v[214:215] op_sel:[0,1,0] neg_lo:[1,0,0] neg_hi:[1,0,0]
	v_readlane_b32 s10, v42, 57
	v_readlane_b32 s11, v43, 57
	v_pk_fma_f32 v[212:213], s[4:5], v[50:51], v[212:213] op_sel_hi:[1,0,1] neg_lo:[1,0,0] neg_hi:[1,0,0]
	v_readlane_b32 s98, v42, 58
	v_readlane_b32 s99, v43, 58
	v_pk_fma_f32 v[214:215], s[6:7], v[50:51], v[214:215] op_sel:[0,1,0] neg_lo:[1,0,0] neg_hi:[1,0,0]
	v_readlane_b32 s2, v42, 59
	v_readlane_b32 s3, v43, 59
	v_pk_fma_f32 v[212:213], s[8:9], v[52:53], v[212:213] op_sel_hi:[1,0,1] neg_lo:[1,0,0] neg_hi:[1,0,0]
	v_readlane_b32 s4, v42, 60
	v_readlane_b32 s5, v43, 60
	v_pk_fma_f32 v[214:215], s[10:11], v[52:53], v[214:215] op_sel:[0,1,0] neg_lo:[1,0,0] neg_hi:[1,0,0]
	v_readlane_b32 s6, v42, 61
	v_readlane_b32 s7, v43, 61
	v_pk_fma_f32 v[212:213], s[98:99], v[54:55], v[212:213] op_sel_hi:[1,0,1] neg_lo:[1,0,0] neg_hi:[1,0,0]
	v_readlane_b32 s8, v43, 62
	v_pk_fma_f32 v[214:215], s[2:3], v[54:55], v[214:215] op_sel:[0,1,0] neg_lo:[1,0,0] neg_hi:[1,0,0]
	v_pk_fma_f32 v[212:213], s[4:5], v[56:57], v[212:213] op_sel_hi:[1,0,1] neg_lo:[1,0,0] neg_hi:[1,0,0]
	v_pk_fma_f32 v[214:215], s[6:7], v[56:57], v[214:215] op_sel:[0,1,0] neg_lo:[1,0,0] neg_hi:[1,0,0]
	v_add_f32_e32 v58, v212, v214
	v_cvt_pk_bf16_f32 v1, -v58, v58
	ds_write_b16 v186, v1 offset:896
	v_fma_f32 v213, -s8, v58, v213
	v_add_f32_e32 v59, v213, v215
	v_cvt_pk_bf16_f32 v1, -v59, v59
	ds_write_b16 v186, v1 offset:960
	ds_write_b16 v186, v174
	s_or_b64 exec, exec, s[24:25]
	s_branch .LBB0_90
